# 128x128 GEMM loops issue their LDS-DMA loads at the top of each k-step; NSA selected/window sweeps read all 8 K fragments before the QK MFMAs
# speedup vs baseline: 1.0595x; 1.0001x over previous
.LBB0_123:
	s_lshl_b32 s2, s20, 10
	s_add_i32 s2, s15, s2
	v_readlane_b32 s72, v250, 53
	v_mov_b32_e32 v60, v200
	s_lshl_b64 s[8:9], s[2:3], 11
	v_readlane_b32 s80, v250, 61
	v_readlane_b32 s81, v250, 62
	v_ashrrev_i32_e32 v36, 3, v60
	v_lshlrev_b32_e32 v0, 3, v60
	s_add_u32 s8, s80, s8
	v_and_b32_e32 v181, 56, v0
	v_add_u32_e32 v42, 32, v36
	v_add_u32_e32 v48, 64, v36
	v_add_u32_e32 v54, 0x60, v36
	s_addc_u32 s9, s81, s9
	v_lshlrev_b32_e32 v196, 1, v181
	v_ashrrev_i32_e32 v37, 31, v36
	v_ashrrev_i32_e32 v43, 31, v42
	v_ashrrev_i32_e32 v49, 31, v48
	v_ashrrev_i32_e32 v55, 31, v54
	v_lshl_add_u64 v[128:129], s[6:7], 0, v[196:197]
	v_lshl_add_u64 v[130:131], s[8:9], 0, v[196:197]
	v_lshlrev_b64 v[132:133], 11, v[36:37]
	v_lshlrev_b64 v[134:135], 11, v[42:43]
	v_lshlrev_b64 v[136:137], 11, v[48:49]
	v_lshlrev_b64 v[138:139], 11, v[54:55]
	v_lshl_add_u64 v[38:39], v[128:129], 0, v[132:133]
	v_lshl_add_u64 v[40:41], v[130:131], 0, v[132:133]
	v_lshl_add_u64 v[44:45], v[128:129], 0, v[134:135]
	v_lshl_add_u64 v[46:47], v[130:131], 0, v[134:135]
	v_lshl_add_u64 v[50:51], v[128:129], 0, v[136:137]
	v_lshl_add_u64 v[52:53], v[130:131], 0, v[136:137]
	v_lshl_add_u64 v[56:57], v[128:129], 0, v[138:139]
	v_lshl_add_u64 v[58:59], v[130:131], 0, v[138:139]
	v_and_b32_e32 v242, 63, v200
	v_readfirstlane_b32 s41, v200
	v_lshrrev_b32_e32 v243, 3, v242
	v_and_b32_e32 v244, 7, v242
	v_lshrrev_b32_e32 v246, 4, v242
	s_lshr_b32 s41, s41, 6
	v_xor_b32_e32 v244, v244, v246
	v_lshlrev_b32_e32 v244, 4, v244
	v_xor_b32_e32 v246, 64, v244
	s_lshl_b32 s46, s41, 5
	v_add_u32_e32 v243, s46, v243
	v_lshlrev_b32_e32 v247, 11, v243
	v_add_u32_e32 v186, v247, v244
	v_add_u32_e32 v187, v247, v246
	v_add_u32_e32 v188, 0x8000, v186
	v_add_u32_e32 v189, 0x8000, v187
	v_add_u32_e32 v187, 0x4000, v187
	v_add_u32_e32 v189, 0x4000, v189
	v_and_b32_e32 v243, 31, v242
	v_lshrrev_b32_e32 v244, 5, v242
	v_bfe_u32 v246, v242, 1, 3
	v_xor_b32_e32 v244, v244, v246
	v_lshlrev_b32_e32 v244, 4, v244
	v_lshl_add_u32 v244, v243, 7, v244
	s_lshr_b32 s46, s41, 1
	s_lshl_b32 s46, s46, 13
	v_add_u32_e32 v190, s46, v244
	s_and_b32 s46, s41, 1
	s_lshl_b32 s46, s46, 13
	s_add_u32 s46, s46, 0x4000
	v_add_u32_e32 v194, s46, v244
	v_xor_b32_e32 v191, 32, v190
	v_xor_b32_e32 v201, 32, v194
	v_xor_b32_e32 v192, 64, v190
	v_xor_b32_e32 v206, 64, v194
	v_xor_b32_e32 v193, 96, v190
	v_xor_b32_e32 v214, 96, v194
	s_lshl_b32 s46, s41, 12
	s_add_u32 s47, s46, 0x4000
	s_mov_b32 s42, s6
	s_mov_b32 s43, s7
	s_mov_b32 s44, s8
	s_mov_b32 s45, s9
	s_add_u32 m0, s46, 0x0
	s_nop 0
	global_load_lds_dwordx4 v186, s[42:43]
	s_add_u32 m0, m0, 0x400
	s_nop 0
	global_load_lds_dwordx4 v187, s[42:43]
	s_add_u32 m0, m0, 0x400
	s_nop 0
	global_load_lds_dwordx4 v188, s[42:43]
	s_add_u32 m0, m0, 0x400
	s_nop 0
	global_load_lds_dwordx4 v189, s[42:43]
	s_add_u32 m0, s46, 0x4000
	s_nop 0
	global_load_lds_dwordx4 v186, s[44:45]
	s_add_u32 m0, m0, 0x400
	s_nop 0
	global_load_lds_dwordx4 v187, s[44:45]
	s_add_u32 m0, m0, 0x400
	s_nop 0
	global_load_lds_dwordx4 v188, s[44:45]
	s_add_u32 m0, m0, 0x400
	s_nop 0
	global_load_lds_dwordx4 v189, s[44:45]
	s_add_u32 s42, s42, 128
	s_addc_u32 s43, s43, 0
	s_add_u32 s44, s44, 128
	s_addc_u32 s45, s45, 0
	v_and_b32_e32 v61, 31, v60
	v_lshrrev_b32_e32 v62, 1, v60
	v_and_b32_e32 v60, 0x5f, v60
	s_movk_i32 s2, 0x90
	s_mov_b32 s26, 0xfffffc0
	v_and_or_b32 v61, v62, s26, v61
	v_and_b32_e32 v62, 16, v62
	v_mad_u32_u24 v60, v60, s2, 0
	v_mul_lo_u32 v63, v36, s2
	v_mul_lo_u32 v61, v61, s2
	v_add_u32_e32 v182, v60, v62
	v_add_u32_e32 v60, 0, v196
	v_lshlrev_b64 v[36:37], 10, v[36:37]
	v_add_u32_e32 v96, 0x1200, v63
	v_lshlrev_b64 v[42:43], 10, v[42:43]
	v_lshlrev_b64 v[48:49], 10, v[48:49]
	v_lshlrev_b64 v[54:55], 10, v[54:55]
	v_add_u32_e32 v38, 0, v61
	v_add_u32_e32 v183, v60, v63
	s_mov_b32 s21, 0
	s_movk_i32 s22, 0x80
	v_mov_b32_e32 v0, 0
	v_mov_b32_e32 v1, v172
	v_mov_b32_e32 v2, v172
	v_mov_b32_e32 v3, v172
	v_lshlrev_b64 v[140:141], 1, v[36:37]
	v_add_u32_e32 v184, v60, v96
	v_lshlrev_b64 v[142:143], 1, v[42:43]
	v_lshlrev_b64 v[144:145], 1, v[48:49]
	v_lshlrev_b64 v[146:147], 1, v[54:55]
	v_add_u32_e32 v185, v38, v62
	v_mov_b32_e32 v36, v172
	v_mov_b32_e32 v37, v172
	v_mov_b32_e32 v38, v172
	v_mov_b32_e32 v39, v172
	v_mov_b32_e32 v40, v172
	v_mov_b32_e32 v41, v172
	v_mov_b32_e32 v42, v172
	v_mov_b32_e32 v43, v172
	v_mov_b32_e32 v44, v172
	v_mov_b32_e32 v45, v172
	v_mov_b32_e32 v46, v172
	v_mov_b32_e32 v4, v172
	v_mov_b32_e32 v5, v172
	v_mov_b32_e32 v6, v172
	v_mov_b32_e32 v7, v172
	v_mov_b32_e32 v8, v172
	v_mov_b32_e32 v9, v172
	v_mov_b32_e32 v10, v172
	v_mov_b32_e32 v11, v172
	v_mov_b32_e32 v12, v172
	v_mov_b32_e32 v13, v172
	v_mov_b32_e32 v14, v172
	v_mov_b32_e32 v15, v172
	v_mov_b32_e32 v16, 0
	v_mov_b32_e32 v17, v172
	v_mov_b32_e32 v18, v172
	v_mov_b32_e32 v19, v172
	v_mov_b32_e32 v20, v172
	v_mov_b32_e32 v21, v172
	v_mov_b32_e32 v22, v172
	v_mov_b32_e32 v23, v172
	v_mov_b32_e32 v24, v172
	v_mov_b32_e32 v25, v172
	v_mov_b32_e32 v26, v172
	v_mov_b32_e32 v27, v172
	v_mov_b32_e32 v28, v172
	v_mov_b32_e32 v29, v172
	v_mov_b32_e32 v30, v172
	v_mov_b32_e32 v31, v172
	v_mov_b32_e32 v32, 0
	v_mov_b32_e32 v33, v172
	v_mov_b32_e32 v34, v172
	v_mov_b32_e32 v35, v172
	v_mov_b32_e32 v47, v172
	v_mov_b32_e32 v48, 0
	v_mov_b32_e32 v49, v172
	v_mov_b32_e32 v50, v172
	v_mov_b32_e32 v51, v172
	v_mov_b32_e32 v52, v172
	v_mov_b32_e32 v53, v172
	v_mov_b32_e32 v54, v172
	v_mov_b32_e32 v55, v172
	v_mov_b32_e32 v56, v172
	v_mov_b32_e32 v57, v172
	v_mov_b32_e32 v58, v172
	v_mov_b32_e32 v59, v172
	v_mov_b32_e32 v60, v172
	v_mov_b32_e32 v61, v172
	v_mov_b32_e32 v62, v172
	v_mov_b32_e32 v63, v172
	v_readlane_b32 s73, v250, 54
	v_readlane_b32 s74, v250, 55
	v_readlane_b32 s75, v250, 56
	v_readlane_b32 s76, v250, 57
	v_readlane_b32 s77, v250, 58
	v_readlane_b32 s78, v250, 59
	v_readlane_b32 s79, v250, 60
	v_readlane_b32 s82, v250, 63
	v_readlane_b32 s83, v249, 0
	v_readlane_b32 s84, v249, 1
	v_readlane_b32 s85, v249, 2
	v_readlane_b32 s86, v249, 3
	v_readlane_b32 s87, v249, 4
	s_mov_b32 s49, 0x8000
	s_waitcnt vmcnt(0)
	s_waitcnt lgkmcnt(0)
	s_barrier
	s_branch .LBB0_125
.LBB0_125:
	ds_read_b128 v[64:67], v194
	ds_read_b128 v[68:71], v190
	ds_read_b128 v[72:75], v194 offset:4096
	ds_read_b128 v[76:79], v190 offset:4096
	ds_read_b128 v[80:83], v201
	ds_read_b128 v[84:87], v191
	ds_read_b128 v[88:91], v201 offset:4096
	ds_read_b128 v[92:95], v191 offset:4096
	ds_read_b128 v[96:99], v206
	ds_read_b128 v[100:103], v192
	ds_read_b128 v[104:107], v206 offset:4096
	ds_read_b128 v[108:111], v192 offset:4096
	ds_read_b128 v[112:115], v214
	ds_read_b128 v[116:119], v193
	ds_read_b128 v[120:123], v214 offset:4096
	ds_read_b128 v[124:127], v193 offset:4096
	s_add_u32 m0, s46, s49
	s_nop 0
	global_load_lds_dwordx4 v186, s[42:43]
	s_add_u32 m0, m0, 0x400
	s_nop 0
	global_load_lds_dwordx4 v187, s[42:43]
	s_add_u32 m0, m0, 0x400
	s_nop 0
	global_load_lds_dwordx4 v188, s[42:43]
	s_add_u32 m0, m0, 0x400
	s_nop 0
	global_load_lds_dwordx4 v189, s[42:43]
	s_add_u32 m0, s47, s49
	s_nop 0
	global_load_lds_dwordx4 v186, s[44:45]
	s_add_u32 m0, m0, 0x400
	s_nop 0
	global_load_lds_dwordx4 v187, s[44:45]
	s_add_u32 m0, m0, 0x400
	s_nop 0
	global_load_lds_dwordx4 v188, s[44:45]
	s_add_u32 m0, m0, 0x400
	s_nop 0
	global_load_lds_dwordx4 v189, s[44:45]
	s_waitcnt lgkmcnt(14)
	v_mfma_f32_32x32x16_bf16 v[48:63], v[64:67], v[68:71], v[48:63]
	s_waitcnt lgkmcnt(13)
	v_mfma_f32_32x32x16_bf16 v[32:47], v[72:75], v[68:71], v[32:47]
	s_waitcnt lgkmcnt(12)
	v_mfma_f32_32x32x16_bf16 v[16:31], v[64:67], v[76:79], v[16:31]
	v_mfma_f32_32x32x16_bf16 v[0:15], v[72:75], v[76:79], v[0:15]
	s_waitcnt lgkmcnt(10)
	v_mfma_f32_32x32x16_bf16 v[48:63], v[80:83], v[84:87], v[48:63]
	s_waitcnt lgkmcnt(9)
	v_mfma_f32_32x32x16_bf16 v[32:47], v[88:91], v[84:87], v[32:47]
	s_waitcnt lgkmcnt(8)
	v_mfma_f32_32x32x16_bf16 v[16:31], v[80:83], v[92:95], v[16:31]
	v_mfma_f32_32x32x16_bf16 v[0:15], v[88:91], v[92:95], v[0:15]
	s_waitcnt lgkmcnt(6)
	v_mfma_f32_32x32x16_bf16 v[48:63], v[96:99], v[100:103], v[48:63]
	s_waitcnt lgkmcnt(5)
	v_mfma_f32_32x32x16_bf16 v[32:47], v[104:107], v[100:103], v[32:47]
	s_waitcnt lgkmcnt(4)
	v_mfma_f32_32x32x16_bf16 v[16:31], v[96:99], v[108:111], v[16:31]
	v_mfma_f32_32x32x16_bf16 v[0:15], v[104:107], v[108:111], v[0:15]
	s_waitcnt lgkmcnt(2)
	v_mfma_f32_32x32x16_bf16 v[48:63], v[112:115], v[116:119], v[48:63]
	s_waitcnt lgkmcnt(1)
	v_mfma_f32_32x32x16_bf16 v[32:47], v[120:123], v[116:119], v[32:47]
	s_waitcnt lgkmcnt(0)
	v_mfma_f32_32x32x16_bf16 v[16:31], v[112:115], v[124:127], v[16:31]
	v_mfma_f32_32x32x16_bf16 v[0:15], v[120:123], v[124:127], v[0:15]
	v_xor_b32_e32 v190, 0x8000, v190
	v_xor_b32_e32 v191, 0x8000, v191
	v_xor_b32_e32 v192, 0x8000, v192
	v_xor_b32_e32 v193, 0x8000, v193
	v_xor_b32_e32 v194, 0x8000, v194
	v_xor_b32_e32 v201, 0x8000, v201
	v_xor_b32_e32 v206, 0x8000, v206
	v_xor_b32_e32 v214, 0x8000, v214
	s_xor_b32 s49, s49, 0x8000
	s_add_u32 s42, s42, 128
	s_addc_u32 s43, s43, 0
	s_add_u32 s44, s44, 128
	s_addc_u32 s45, s45, 0
	s_add_u32 s21, s21, 1
	s_waitcnt vmcnt(0)
	s_cmp_lt_u32 s21, 15
	s_barrier
	s_cbranch_scc1 .LBB0_125

.LBB0_317:
	v_lshl_add_u32 v2, s0, 6, v203
	s_movk_i32 s13, 0x1400
	v_mad_i64_i32 v[0:1], s[0:1], v2, s13, 0
	v_or_b32_e32 v0, v0, v148
	v_lshl_add_u64 v[0:1], v[0:1], 1, v[146:147]
	global_load_dwordx4 v[128:131], v[0:1], off offset:3072
	global_load_dwordx4 v[132:135], v[0:1], off offset:3584
	v_add_u32_e32 v0, 32, v2
	v_mad_i64_i32 v[0:1], s[0:1], v0, s13, 0
	v_or_b32_e32 v0, v0, v148
	v_lshl_add_u64 v[0:1], v[0:1], 1, v[146:147]
	global_load_dwordx4 v[136:139], v[0:1], off offset:3072
	global_load_dwordx4 v[140:143], v[0:1], off offset:3584
	v_add3_u32 v8, v178, v201, v202
	ds_read_b128 v[0:3], v8
	ds_read_b128 v[4:7], v8 offset:32
	ds_read_b128 v[12:15], v8 offset:64
	ds_read_b128 v[16:19], v8 offset:96
	ds_read_b128 v[20:23], v8 offset:4608
	ds_read_b128 v[24:27], v8 offset:4640
	ds_read_b128 v[28:31], v8 offset:4672
	ds_read_b128 v[8:11], v8 offset:4704
	s_mov_b64 s[14:15], -1
	s_cmp_lg_u32 s51, s20
	s_waitcnt lgkmcnt(7)
	v_mfma_f32_32x32x16_bf16 v[112:127], v[0:3], v[160:163], 0
	s_waitcnt lgkmcnt(6)
	v_mfma_f32_32x32x16_bf16 v[112:127], v[4:7], v[164:167], v[112:127]
	s_waitcnt lgkmcnt(5)
	v_mfma_f32_32x32x16_bf16 v[112:127], v[12:15], v[168:171], v[112:127]
	s_waitcnt lgkmcnt(4)
	v_mfma_f32_32x32x16_bf16 v[112:127], v[16:19], v[172:175], v[112:127]
	s_waitcnt lgkmcnt(3)
	v_mfma_f32_32x32x16_bf16 v[96:111], v[20:23], v[160:163], 0
	s_waitcnt lgkmcnt(2)
	v_mfma_f32_32x32x16_bf16 v[96:111], v[24:27], v[164:167], v[96:111]
	s_waitcnt lgkmcnt(1)
	v_mfma_f32_32x32x16_bf16 v[96:111], v[28:31], v[168:171], v[96:111]
	s_waitcnt lgkmcnt(0)
	v_mfma_f32_32x32x16_bf16 v[96:111], v[8:11], v[172:175], v[96:111]
	s_cbranch_scc0 .LBB0_319
	s_nop 10
	v_max_f32_e32 v0, v96, v96
	v_max_f32_e32 v1, v112, v112
	v_max_f32_e32 v0, v1, v0
	v_max3_f32 v0, v0, v113, v97
	v_max3_f32 v0, v0, v114, v98
	v_max3_f32 v0, v0, v115, v99
	v_max3_f32 v0, v0, v116, v100
	v_max3_f32 v0, v0, v117, v101
	v_max3_f32 v0, v0, v118, v102
	v_max3_f32 v0, v0, v119, v103
	v_max3_f32 v0, v0, v120, v104
	v_max3_f32 v0, v0, v121, v105
	v_max3_f32 v0, v0, v122, v106
	v_max3_f32 v0, v0, v123, v107
	v_max3_f32 v0, v0, v124, v108
	v_max3_f32 v0, v0, v125, v109
	v_max3_f32 v0, v0, v126, v110
	v_max3_f32 v0, v0, v127, v111
	ds_bpermute_b32 v1, v176, v0
	v_bfe_u32 v2, v154, s51, 1
	v_cmp_eq_u32_e32 vcc, 0, v2
	v_max_f32_e32 v3, v180, v180
	s_mov_b64 s[14:15], 0
	s_waitcnt lgkmcnt(0)
	v_max_f32_e32 v1, v1, v1
	v_max_f32_e32 v0, v0, v1
	v_mul_f32_e32 v0, 0x3e38aa3b, v0
	v_cndmask_b32_e32 v0, v0, v215, vcc
	v_max_f32_e32 v181, v3, v0
	v_sub_f32_e32 v0, v180, v181
	v_cndmask_b32_e64 v30, v232, 0, vcc
	v_cndmask_b32_e64 v182, -v181, v215, vcc
	v_exp_f32_e32 v150, v0
	v_pk_fma_f32 v[0:1], v[30:31], v[112:113], v[182:183] op_sel_hi:[0,1,0]
	v_exp_f32_e32 v0, v0
	v_exp_f32_e32 v1, v1
	v_pk_fma_f32 v[2:3], v[30:31], v[114:115], v[182:183] op_sel_hi:[0,1,0]
	v_exp_f32_e32 v2, v2
	v_exp_f32_e32 v3, v3
	v_pk_fma_f32 v[4:5], v[30:31], v[116:117], v[182:183] op_sel_hi:[0,1,0]
	v_exp_f32_e32 v4, v4
	v_exp_f32_e32 v5, v5
	v_pk_fma_f32 v[6:7], v[30:31], v[118:119], v[182:183] op_sel_hi:[0,1,0]
	v_exp_f32_e32 v6, v6
	v_exp_f32_e32 v7, v7
	v_pk_add_f32 v[8:9], v[0:1], 0 op_sel_hi:[1,0]
	v_pk_fma_f32 v[10:11], v[30:31], v[122:123], v[182:183] op_sel_hi:[0,1,0]
	v_pk_add_f32 v[8:9], v[2:3], v[8:9]
	v_exp_f32_e32 v10, v10
	v_pk_add_f32 v[8:9], v[4:5], v[8:9]
	v_exp_f32_e32 v11, v11
	v_pk_add_f32 v[16:17], v[6:7], v[8:9]
	v_pk_fma_f32 v[8:9], v[30:31], v[120:121], v[182:183] op_sel_hi:[0,1,0]
	v_exp_f32_e32 v8, v8
	v_exp_f32_e32 v9, v9
	v_pk_fma_f32 v[12:13], v[30:31], v[124:125], v[182:183] op_sel_hi:[0,1,0]
	v_exp_f32_e32 v12, v12
	v_exp_f32_e32 v13, v13
	v_pk_fma_f32 v[14:15], v[30:31], v[126:127], v[182:183] op_sel_hi:[0,1,0]
	v_exp_f32_e32 v14, v14
	v_exp_f32_e32 v15, v15
	v_pk_add_f32 v[16:17], v[8:9], v[16:17]
	v_pk_fma_f32 v[18:19], v[30:31], v[98:99], v[182:183] op_sel_hi:[0,1,0]
	v_pk_add_f32 v[16:17], v[10:11], v[16:17]
	v_exp_f32_e32 v18, v18
	v_pk_add_f32 v[16:17], v[12:13], v[16:17]
	v_exp_f32_e32 v19, v19
	v_pk_add_f32 v[24:25], v[14:15], v[16:17]
	v_pk_fma_f32 v[16:17], v[30:31], v[96:97], v[182:183] op_sel_hi:[0,1,0]
	v_exp_f32_e32 v16, v16
	v_exp_f32_e32 v17, v17
	v_pk_fma_f32 v[20:21], v[30:31], v[100:101], v[182:183] op_sel_hi:[0,1,0]
	v_exp_f32_e32 v20, v20
	v_exp_f32_e32 v21, v21
	v_pk_fma_f32 v[22:23], v[30:31], v[102:103], v[182:183] op_sel_hi:[0,1,0]
	v_exp_f32_e32 v22, v22
	v_exp_f32_e32 v23, v23
	v_pk_add_f32 v[24:25], v[16:17], v[24:25]
	v_pk_fma_f32 v[26:27], v[30:31], v[106:107], v[182:183] op_sel_hi:[0,1,0]
	v_pk_add_f32 v[24:25], v[18:19], v[24:25]
	v_exp_f32_e32 v26, v26
	v_pk_add_f32 v[24:25], v[20:21], v[24:25]
	v_exp_f32_e32 v27, v27
	v_pk_add_f32 v[184:185], v[22:23], v[24:25]
	v_pk_fma_f32 v[24:25], v[30:31], v[104:105], v[182:183] op_sel_hi:[0,1,0]
	v_exp_f32_e32 v24, v24
	v_exp_f32_e32 v25, v25
	v_pk_fma_f32 v[28:29], v[30:31], v[108:109], v[182:183] op_sel_hi:[0,1,0]
	v_exp_f32_e32 v28, v28
	v_exp_f32_e32 v29, v29
	v_pk_fma_f32 v[30:31], v[30:31], v[110:111], v[182:183] op_sel_hi:[0,1,0]
	v_exp_f32_e32 v30, v30
	v_exp_f32_e32 v31, v31
	v_pk_add_f32 v[182:183], v[24:25], v[184:185]
	s_nop 0
	v_pk_add_f32 v[182:183], v[26:27], v[182:183]
	s_nop 0
	v_pk_add_f32 v[182:183], v[28:29], v[182:183]
	s_nop 0
	v_pk_add_f32 v[182:183], v[30:31], v[182:183]
	s_nop 0
	v_add_f32_e32 v182, v182, v183

.LBB0_326:
	s_mov_b32 s4, s0
	s_add_i32 s0, s0, 1
	s_cmp_gt_i32 s0, s1
	s_cselect_b64 s[6:7], -1, 0
	s_cmp_le_i32 s0, s1
	s_movk_i32 s5, 0x4800
	s_cselect_b64 s[8:9], -1, 0
	v_mul_lo_u32 v0, v241, s5
	s_and_b64 s[12:13], s[8:9], exec
	v_add_u32_e32 v242, 0, v0
	s_cselect_b32 s5, s0, s4
	v_add3_u32 v0, v242, v235, v239
	v_lshl_add_u32 v2, s5, 6, v203
	s_movk_i32 s5, 0x1400
	s_waitcnt vmcnt(3)
	ds_write_b128 v0, v[176:179]
	s_waitcnt vmcnt(2)
	ds_write_b128 v0, v[180:183] offset:9216
	s_waitcnt vmcnt(1)
	ds_write_b128 v0, v[184:187] offset:4608
	s_waitcnt vmcnt(0)
	ds_write_b128 v0, v[188:191] offset:13824
	v_mad_i64_i32 v[0:1], s[12:13], v2, s5, 0
	v_or_b32_e32 v0, v0, v214
	v_lshl_add_u64 v[0:1], v[0:1], 1, v[212:213]
	s_waitcnt lgkmcnt(0)
	s_barrier
	global_load_dwordx4 v[176:179], v[0:1], off
	global_load_dwordx4 v[180:183], v[0:1], off offset:512
	v_add_u32_e32 v0, 32, v2
	v_mad_i64_i32 v[0:1], s[12:13], v0, s5, 0
	v_or_b32_e32 v0, v0, v214
	v_lshl_add_u64 v[0:1], v[0:1], 1, v[212:213]
	global_load_dwordx4 v[184:187], v[0:1], off
	global_load_dwordx4 v[188:191], v[0:1], off offset:512
	v_add3_u32 v8, v242, v201, v202
	ds_read_b128 v[0:3], v8
	ds_read_b128 v[4:7], v8 offset:32
	ds_read_b128 v[12:15], v8 offset:64
	ds_read_b128 v[16:19], v8 offset:96
	ds_read_b128 v[20:23], v8 offset:4608
	ds_read_b128 v[24:27], v8 offset:4640
	ds_read_b128 v[28:31], v8 offset:4672
	ds_read_b128 v[8:11], v8 offset:4704
	s_cmp_eq_u32 s20, s4
	s_cselect_b64 s[4:5], -1, 0
	s_cmp_lt_i32 s10, s2
	s_cselect_b64 s[12:13], -1, 0
	s_or_b64 s[12:13], s[4:5], s[12:13]
	s_mov_b64 s[4:5], -1
	s_andn2_b64 vcc, exec, s[12:13]
	s_waitcnt lgkmcnt(7)
	v_mfma_f32_32x32x16_bf16 v[144:159], v[0:3], v[160:163], 0
	s_waitcnt lgkmcnt(6)
	v_mfma_f32_32x32x16_bf16 v[144:159], v[4:7], v[164:167], v[144:159]
	s_waitcnt lgkmcnt(5)
	v_mfma_f32_32x32x16_bf16 v[144:159], v[12:15], v[168:171], v[144:159]
	s_waitcnt lgkmcnt(4)
	v_mfma_f32_32x32x16_bf16 v[144:159], v[16:19], v[172:175], v[144:159]
	s_waitcnt lgkmcnt(3)
	v_mfma_f32_32x32x16_bf16 v[128:143], v[20:23], v[160:163], 0
	s_waitcnt lgkmcnt(2)
	v_mfma_f32_32x32x16_bf16 v[128:143], v[24:27], v[164:167], v[128:143]
	s_waitcnt lgkmcnt(1)
	v_mfma_f32_32x32x16_bf16 v[128:143], v[28:31], v[168:171], v[128:143]
	s_waitcnt lgkmcnt(0)
	v_mfma_f32_32x32x16_bf16 v[128:143], v[8:11], v[172:175], v[128:143]
	s_cbranch_vccz .LBB0_328
	s_nop 10
	v_max_f32_e32 v0, v128, v128
	v_max_f32_e32 v1, v144, v144
	v_max_f32_e32 v0, v1, v0
	v_max3_f32 v0, v0, v145, v129
	v_max3_f32 v0, v0, v146, v130
	v_max3_f32 v0, v0, v147, v131
	v_max3_f32 v0, v0, v148, v132
	v_max3_f32 v0, v0, v149, v133
	v_max3_f32 v0, v0, v150, v134
	v_max3_f32 v0, v0, v151, v135
	v_max3_f32 v0, v0, v152, v136
	v_max3_f32 v0, v0, v153, v137
	v_max3_f32 v0, v0, v154, v138
	v_max3_f32 v0, v0, v155, v139
	v_max3_f32 v0, v0, v156, v140
	v_max3_f32 v0, v0, v157, v141
	v_max3_f32 v0, v0, v158, v142
	v_max3_f32 v0, v0, v159, v143
	ds_bpermute_b32 v1, v240, v0
	s_mov_b32 s4, 0x3e38aa3b
	s_waitcnt lgkmcnt(0)
	v_max_f32_e32 v1, v1, v1
	v_max_f32_e32 v0, v0, v1
	v_mul_f32_e32 v0, 0x3e38aa3b, v0
	v_max_f32_e32 v1, v244, v244
	v_max_f32_e32 v216, v1, v0
	v_pk_fma_f32 v[0:1], v[144:145], s[4:5], v[216:217] op_sel_hi:[1,0,0] neg_lo:[0,0,1] neg_hi:[0,0,1]
	v_pk_fma_f32 v[2:3], v[146:147], s[4:5], v[216:217] op_sel_hi:[1,0,0] neg_lo:[0,0,1] neg_hi:[0,0,1]
	v_exp_f32_e32 v0, v0
	v_exp_f32_e32 v1, v1
	v_exp_f32_e32 v2, v2
	v_exp_f32_e32 v3, v3
	v_sub_f32_e32 v218, v244, v216
	v_pk_add_f32 v[4:5], v[0:1], 0 op_sel_hi:[1,0]
	v_exp_f32_e32 v218, v218
	v_pk_add_f32 v[6:7], v[2:3], v[4:5]
	v_pk_fma_f32 v[4:5], v[148:149], s[4:5], v[216:217] op_sel_hi:[1,0,0] neg_lo:[0,0,1] neg_hi:[0,0,1]
	s_nop 0
	v_exp_f32_e32 v4, v4
	v_exp_f32_e32 v5, v5
	s_nop 0
	v_pk_add_f32 v[8:9], v[4:5], v[6:7]
	v_pk_fma_f32 v[6:7], v[150:151], s[4:5], v[216:217] op_sel_hi:[1,0,0] neg_lo:[0,0,1] neg_hi:[0,0,1]
	s_nop 0
	v_exp_f32_e32 v6, v6
	v_exp_f32_e32 v7, v7
	s_nop 0
	v_pk_add_f32 v[10:11], v[6:7], v[8:9]
	v_pk_fma_f32 v[8:9], v[152:153], s[4:5], v[216:217] op_sel_hi:[1,0,0] neg_lo:[0,0,1] neg_hi:[0,0,1]
	s_nop 0
	v_exp_f32_e32 v8, v8
	v_exp_f32_e32 v9, v9
	s_nop 0
	v_pk_add_f32 v[12:13], v[8:9], v[10:11]
	v_pk_fma_f32 v[10:11], v[154:155], s[4:5], v[216:217] op_sel_hi:[1,0,0] neg_lo:[0,0,1] neg_hi:[0,0,1]
	s_nop 0
	v_exp_f32_e32 v10, v10
	v_exp_f32_e32 v11, v11
	s_nop 0
	v_pk_add_f32 v[14:15], v[10:11], v[12:13]
	v_pk_fma_f32 v[12:13], v[156:157], s[4:5], v[216:217] op_sel_hi:[1,0,0] neg_lo:[0,0,1] neg_hi:[0,0,1]
	s_nop 0
	v_exp_f32_e32 v12, v12
	v_exp_f32_e32 v13, v13
	s_nop 0
	v_pk_add_f32 v[16:17], v[12:13], v[14:15]
	v_pk_fma_f32 v[14:15], v[158:159], s[4:5], v[216:217] op_sel_hi:[1,0,0] neg_lo:[0,0,1] neg_hi:[0,0,1]
	s_nop 0
	v_exp_f32_e32 v14, v14
	v_exp_f32_e32 v15, v15
	s_nop 0
	v_pk_add_f32 v[18:19], v[14:15], v[16:17]
	v_pk_fma_f32 v[16:17], v[128:129], s[4:5], v[216:217] op_sel_hi:[1,0,0] neg_lo:[0,0,1] neg_hi:[0,0,1]
	s_nop 0
	v_exp_f32_e32 v16, v16
	v_exp_f32_e32 v17, v17
	s_nop 0
	v_pk_add_f32 v[20:21], v[16:17], v[18:19]
	v_pk_fma_f32 v[18:19], v[130:131], s[4:5], v[216:217] op_sel_hi:[1,0,0] neg_lo:[0,0,1] neg_hi:[0,0,1]
	s_nop 0
	v_exp_f32_e32 v18, v18
	v_exp_f32_e32 v19, v19
	s_nop 0
	v_pk_add_f32 v[22:23], v[18:19], v[20:21]
	v_pk_fma_f32 v[20:21], v[132:133], s[4:5], v[216:217] op_sel_hi:[1,0,0] neg_lo:[0,0,1] neg_hi:[0,0,1]
	s_nop 0
	v_exp_f32_e32 v20, v20
	v_exp_f32_e32 v21, v21
	s_nop 0
	v_pk_add_f32 v[24:25], v[20:21], v[22:23]
	v_pk_fma_f32 v[22:23], v[134:135], s[4:5], v[216:217] op_sel_hi:[1,0,0] neg_lo:[0,0,1] neg_hi:[0,0,1]
	s_nop 0
	v_exp_f32_e32 v22, v22
	v_exp_f32_e32 v23, v23
	s_nop 0
	v_pk_add_f32 v[26:27], v[22:23], v[24:25]
	v_pk_fma_f32 v[24:25], v[136:137], s[4:5], v[216:217] op_sel_hi:[1,0,0] neg_lo:[0,0,1] neg_hi:[0,0,1]
	s_nop 0
	v_exp_f32_e32 v24, v24
	v_exp_f32_e32 v25, v25
	s_nop 0
	v_pk_add_f32 v[28:29], v[24:25], v[26:27]
	v_pk_fma_f32 v[26:27], v[138:139], s[4:5], v[216:217] op_sel_hi:[1,0,0] neg_lo:[0,0,1] neg_hi:[0,0,1]
	s_nop 0
	v_exp_f32_e32 v26, v26
	v_exp_f32_e32 v27, v27
	s_nop 0
	v_pk_add_f32 v[30:31], v[26:27], v[28:29]
	v_pk_fma_f32 v[28:29], v[140:141], s[4:5], v[216:217] op_sel_hi:[1,0,0] neg_lo:[0,0,1] neg_hi:[0,0,1]
	s_nop 0
	v_exp_f32_e32 v28, v28
	v_exp_f32_e32 v29, v29
	s_nop 0
	v_pk_add_f32 v[246:247], v[28:29], v[30:31]
	v_pk_fma_f32 v[30:31], v[142:143], s[4:5], v[216:217] op_sel_hi:[1,0,0] neg_lo:[0,0,1] neg_hi:[0,0,1]
	s_mov_b64 s[4:5], 0
	v_exp_f32_e32 v30, v30
	v_exp_f32_e32 v31, v31
	s_nop 0
	v_pk_add_f32 v[246:247], v[30:31], v[246:247]
	s_nop 0
	v_add_f32_e32 v245, v246, v247

.LBB0_416:
	s_and_b32 s0, s0, 15
	s_or_b32 s18, s0, s50
	v_readlane_b32 s72, v250, 53
	s_lshl_b32 s0, s18, 18
	v_readlane_b32 s78, v250, 59
	v_readlane_b32 s79, v250, 60
	s_add_u32 s4, s78, s0
	v_mov_b32_e32 v3, v200
	v_readlane_b32 s80, v250, 61
	s_addc_u32 s5, s79, 0
	s_lshl_b32 s0, s17, 18
	v_ashrrev_i32_e32 v36, 3, v3
	v_lshlrev_b32_e32 v0, 3, v3
	v_readlane_b32 s81, v250, 62
	s_waitcnt vmcnt(0)
	v_and_b32_e32 v148, 56, v0
	s_add_u32 s6, s80, s0
	v_add_u32_e32 v40, 32, v36
	v_add_u32_e32 v44, 64, v36
	v_add_u32_e32 v48, 0x60, v36
	v_lshlrev_b32_e32 v196, 1, v148
	v_ashrrev_i32_e32 v37, 31, v36
	v_ashrrev_i32_e32 v41, 31, v40
	s_addc_u32 s7, s81, 0
	v_ashrrev_i32_e32 v45, 31, v44
	v_ashrrev_i32_e32 v49, 31, v48
	v_lshl_add_u64 v[128:129], s[4:5], 0, v[196:197]
	v_lshlrev_b64 v[130:131], 11, v[36:37]
	v_lshlrev_b64 v[132:133], 11, v[40:41]
	v_lshlrev_b64 v[134:135], 11, v[44:45]
	v_lshlrev_b64 v[136:137], 11, v[48:49]
	v_lshl_add_u64 v[138:139], s[6:7], 0, v[196:197]
	v_lshl_add_u64 v[38:39], v[128:129], 0, v[130:131]
	v_lshl_add_u64 v[42:43], v[128:129], 0, v[132:133]
	v_lshl_add_u64 v[46:47], v[128:129], 0, v[134:135]
	v_lshl_add_u64 v[50:51], v[128:129], 0, v[136:137]
	v_lshl_add_u64 v[52:53], v[138:139], 0, v[130:131]
	v_lshl_add_u64 v[54:55], v[138:139], 0, v[132:133]
	v_and_b32_e32 v184, 63, v200
	v_readfirstlane_b32 s2, v200
	v_lshrrev_b32_e32 v185, 3, v184
	v_and_b32_e32 v186, 7, v184
	v_lshrrev_b32_e32 v187, 4, v184
	s_lshr_b32 s2, s2, 6
	v_xor_b32_e32 v186, v186, v187
	v_lshlrev_b32_e32 v186, 4, v186
	v_xor_b32_e32 v187, 64, v186
	s_lshl_b32 s32, s2, 5
	v_add_u32_e32 v185, s32, v185
	v_lshlrev_b32_e32 v188, 11, v185
	v_add_u32_e32 v166, v188, v186
	v_add_u32_e32 v167, v188, v187
	v_add_u32_e32 v168, 0x8000, v166
	v_add_u32_e32 v169, 0x8000, v167
	v_add_u32_e32 v167, 0x4000, v167
	v_add_u32_e32 v169, 0x4000, v169
	v_and_b32_e32 v185, 31, v184
	v_lshrrev_b32_e32 v186, 5, v184
	v_bfe_u32 v187, v184, 1, 3
	v_xor_b32_e32 v186, v186, v187
	v_lshlrev_b32_e32 v186, 4, v186
	v_lshl_add_u32 v186, v185, 7, v186
	s_lshr_b32 s32, s2, 1
	s_lshl_b32 s32, s32, 13
	v_add_u32_e32 v170, s32, v186
	s_and_b32 s32, s2, 1
	s_lshl_b32 s32, s32, 13
	s_add_u32 s32, s32, 0x4000
	v_add_u32_e32 v174, s32, v186
	v_xor_b32_e32 v171, 32, v170
	v_xor_b32_e32 v175, 32, v174
	v_xor_b32_e32 v172, 64, v170
	v_xor_b32_e32 v176, 64, v174
	v_xor_b32_e32 v173, 96, v170
	v_xor_b32_e32 v177, 96, v174
	s_lshl_b32 s32, s2, 12
	s_add_u32 s49, s32, 0x4000
	s_mov_b32 s8, s4
	s_mov_b32 s9, s5
	s_mov_b32 s46, s6
	s_mov_b32 s47, s7
	s_add_u32 m0, s32, 0x0
	s_nop 0
	global_load_lds_dwordx4 v166, s[8:9]
	s_add_u32 m0, m0, 0x400
	s_nop 0
	global_load_lds_dwordx4 v167, s[8:9]
	s_add_u32 m0, m0, 0x400
	s_nop 0
	global_load_lds_dwordx4 v168, s[8:9]
	s_add_u32 m0, m0, 0x400
	s_nop 0
	global_load_lds_dwordx4 v169, s[8:9]
	s_add_u32 m0, s32, 0x4000
	s_nop 0
	global_load_lds_dwordx4 v166, s[46:47]
	s_add_u32 m0, m0, 0x400
	s_nop 0
	global_load_lds_dwordx4 v167, s[46:47]
	s_add_u32 m0, m0, 0x400
	s_nop 0
	global_load_lds_dwordx4 v168, s[46:47]
	s_add_u32 m0, m0, 0x400
	s_nop 0
	global_load_lds_dwordx4 v169, s[46:47]
	s_add_u32 s8, s8, 128
	s_addc_u32 s9, s9, 0
	s_add_u32 s46, s46, 128
	s_addc_u32 s47, s47, 0
	v_lshl_add_u64 v[56:57], v[138:139], 0, v[134:135]
	v_lshl_add_u64 v[58:59], v[138:139], 0, v[136:137]
	v_and_b32_e32 v60, 31, v3
	v_lshrrev_b32_e32 v61, 1, v3
	v_and_b32_e32 v3, 0x5f, v3
	s_movk_i32 s2, 0x90
	v_and_or_b32 v60, v61, s23, v60
	v_and_b32_e32 v61, 16, v61
	v_mad_u32_u24 v3, v3, s2, 0
	v_mul_lo_u32 v62, v36, s2
	v_mul_lo_u32 v60, v60, s2
	v_add_u32_e32 v149, v3, v61
	v_add_u32_e32 v3, 0, v196
	v_mov_b32_e32 v0, 0
	v_add_u32_e32 v63, 0x1200, v62
	v_lshlrev_b64 v[36:37], 10, v[36:37]
	v_lshlrev_b64 v[40:41], 10, v[40:41]
	v_lshlrev_b64 v[44:45], 10, v[44:45]
	v_lshlrev_b64 v[48:49], 10, v[48:49]
	v_add_u32_e32 v60, 0, v60
	v_add_u32_e32 v150, v3, v62
	s_movk_i32 s0, 0x80
	s_mov_b32 s1, 0
	v_mov_b32_e32 v1, v0
	v_mov_b32_e32 v2, v0
	v_lshlrev_b64 v[140:141], 1, v[36:37]
	v_add_u32_e32 v151, v3, v63
	v_lshlrev_b64 v[142:143], 1, v[40:41]
	v_lshlrev_b64 v[144:145], 1, v[44:45]
	v_lshlrev_b64 v[146:147], 1, v[48:49]
	v_add_u32_e32 v152, v60, v61
	v_mov_b32_e32 v3, v0
	v_mov_b32_e32 v36, v0
	v_mov_b32_e32 v37, v0
	v_mov_b32_e32 v38, v0
	v_mov_b32_e32 v39, v0
	v_mov_b32_e32 v40, v0
	v_mov_b32_e32 v41, v0
	v_mov_b32_e32 v42, v0
	v_mov_b32_e32 v43, v0
	v_mov_b32_e32 v44, v0
	v_mov_b32_e32 v45, v0
	v_mov_b32_e32 v46, v0
	v_mov_b32_e32 v47, v0
	v_mov_b32_e32 v4, v0
	v_mov_b32_e32 v5, v0
	v_mov_b32_e32 v6, v0
	v_mov_b32_e32 v7, v0
	v_mov_b32_e32 v8, v0
	v_mov_b32_e32 v9, v0
	v_mov_b32_e32 v10, v0
	v_mov_b32_e32 v11, v0
	v_mov_b32_e32 v12, v0
	v_mov_b32_e32 v13, v0
	v_mov_b32_e32 v14, v0
	v_mov_b32_e32 v15, v0
	v_mov_b32_e32 v16, v0
	v_mov_b32_e32 v17, v0
	v_mov_b32_e32 v18, v0
	v_mov_b32_e32 v19, v0
	v_mov_b32_e32 v20, v0
	v_mov_b32_e32 v21, v0
	v_mov_b32_e32 v22, v0
	v_mov_b32_e32 v23, v0
	v_mov_b32_e32 v24, v0
	v_mov_b32_e32 v25, v0
	v_mov_b32_e32 v26, v0
	v_mov_b32_e32 v27, v0
	v_mov_b32_e32 v28, v0
	v_mov_b32_e32 v29, v0
	v_mov_b32_e32 v30, v0
	v_mov_b32_e32 v31, v0
	v_mov_b32_e32 v32, v0
	v_mov_b32_e32 v33, v0
	v_mov_b32_e32 v34, v0
	v_mov_b32_e32 v35, v0
	v_mov_b32_e32 v48, v0
	v_mov_b32_e32 v49, v0
	v_mov_b32_e32 v50, v0
	v_mov_b32_e32 v51, v0
	v_mov_b32_e32 v52, v0
	v_mov_b32_e32 v53, v0
	v_mov_b32_e32 v54, v0
	v_mov_b32_e32 v55, v0
	v_mov_b32_e32 v56, v0
	v_mov_b32_e32 v57, v0
	v_mov_b32_e32 v58, v0
	v_mov_b32_e32 v59, v0
	v_mov_b32_e32 v60, v0
	v_mov_b32_e32 v61, v0
	v_mov_b32_e32 v62, v0
	v_mov_b32_e32 v63, v0
	v_readlane_b32 s73, v250, 54
	v_readlane_b32 s74, v250, 55
	v_readlane_b32 s75, v250, 56
	v_readlane_b32 s76, v250, 57
	v_readlane_b32 s77, v250, 58
	v_readlane_b32 s82, v250, 63
	v_readlane_b32 s83, v249, 0
	v_readlane_b32 s84, v249, 1
	v_readlane_b32 s85, v249, 2
	v_readlane_b32 s86, v249, 3
	v_readlane_b32 s87, v249, 4
	s_mov_b32 s0, 0x8000
	s_waitcnt vmcnt(0)
	s_waitcnt lgkmcnt(0)
	s_barrier
	s_branch .LBB0_418
.LBB0_418:
	ds_read_b128 v[64:67], v174
	ds_read_b128 v[68:71], v170
	ds_read_b128 v[72:75], v174 offset:4096
	ds_read_b128 v[76:79], v170 offset:4096
	ds_read_b128 v[80:83], v175
	ds_read_b128 v[84:87], v171
	ds_read_b128 v[88:91], v175 offset:4096
	ds_read_b128 v[92:95], v171 offset:4096
	ds_read_b128 v[96:99], v176
	ds_read_b128 v[100:103], v172
	ds_read_b128 v[104:107], v176 offset:4096
	ds_read_b128 v[108:111], v172 offset:4096
	ds_read_b128 v[112:115], v177
	ds_read_b128 v[116:119], v173
	ds_read_b128 v[120:123], v177 offset:4096
	ds_read_b128 v[124:127], v173 offset:4096
	s_add_u32 m0, s32, s0
	s_nop 0
	global_load_lds_dwordx4 v166, s[8:9]
	s_add_u32 m0, m0, 0x400
	s_nop 0
	global_load_lds_dwordx4 v167, s[8:9]
	s_add_u32 m0, m0, 0x400
	s_nop 0
	global_load_lds_dwordx4 v168, s[8:9]
	s_add_u32 m0, m0, 0x400
	s_nop 0
	global_load_lds_dwordx4 v169, s[8:9]
	s_add_u32 m0, s49, s0
	s_nop 0
	global_load_lds_dwordx4 v166, s[46:47]
	s_add_u32 m0, m0, 0x400
	s_nop 0
	global_load_lds_dwordx4 v167, s[46:47]
	s_add_u32 m0, m0, 0x400
	s_nop 0
	global_load_lds_dwordx4 v168, s[46:47]
	s_add_u32 m0, m0, 0x400
	s_nop 0
	global_load_lds_dwordx4 v169, s[46:47]
	s_waitcnt lgkmcnt(14)
	v_mfma_f32_32x32x16_bf16 v[48:63], v[64:67], v[68:71], v[48:63]
	s_waitcnt lgkmcnt(13)
	v_mfma_f32_32x32x16_bf16 v[32:47], v[72:75], v[68:71], v[32:47]
	s_waitcnt lgkmcnt(12)
	v_mfma_f32_32x32x16_bf16 v[16:31], v[64:67], v[76:79], v[16:31]
	v_mfma_f32_32x32x16_bf16 v[0:15], v[72:75], v[76:79], v[0:15]
	s_waitcnt lgkmcnt(10)
	v_mfma_f32_32x32x16_bf16 v[48:63], v[80:83], v[84:87], v[48:63]
	s_waitcnt lgkmcnt(9)
	v_mfma_f32_32x32x16_bf16 v[32:47], v[88:91], v[84:87], v[32:47]
	s_waitcnt lgkmcnt(8)
	v_mfma_f32_32x32x16_bf16 v[16:31], v[80:83], v[92:95], v[16:31]
	v_mfma_f32_32x32x16_bf16 v[0:15], v[88:91], v[92:95], v[0:15]
	s_waitcnt lgkmcnt(6)
	v_mfma_f32_32x32x16_bf16 v[48:63], v[96:99], v[100:103], v[48:63]
	s_waitcnt lgkmcnt(5)
	v_mfma_f32_32x32x16_bf16 v[32:47], v[104:107], v[100:103], v[32:47]
	s_waitcnt lgkmcnt(4)
	v_mfma_f32_32x32x16_bf16 v[16:31], v[96:99], v[108:111], v[16:31]
	v_mfma_f32_32x32x16_bf16 v[0:15], v[104:107], v[108:111], v[0:15]
	s_waitcnt lgkmcnt(2)
	v_mfma_f32_32x32x16_bf16 v[48:63], v[112:115], v[116:119], v[48:63]
	s_waitcnt lgkmcnt(1)
	v_mfma_f32_32x32x16_bf16 v[32:47], v[120:123], v[116:119], v[32:47]
	s_waitcnt lgkmcnt(0)
	v_mfma_f32_32x32x16_bf16 v[16:31], v[112:115], v[124:127], v[16:31]
	v_mfma_f32_32x32x16_bf16 v[0:15], v[120:123], v[124:127], v[0:15]
	v_xor_b32_e32 v170, 0x8000, v170
	v_xor_b32_e32 v171, 0x8000, v171
	v_xor_b32_e32 v172, 0x8000, v172
	v_xor_b32_e32 v173, 0x8000, v173
	v_xor_b32_e32 v174, 0x8000, v174
	v_xor_b32_e32 v175, 0x8000, v175
	v_xor_b32_e32 v176, 0x8000, v176
	v_xor_b32_e32 v177, 0x8000, v177
	s_xor_b32 s0, s0, 0x8000
	s_add_u32 s8, s8, 128
	s_addc_u32 s9, s9, 0
	s_add_u32 s46, s46, 128
	s_addc_u32 s47, s47, 0
	s_add_u32 s1, s1, 1
	s_waitcnt vmcnt(0)
	s_cmp_lt_u32 s1, 15
	s_barrier
	s_cbranch_scc1 .LBB0_418

.LBB0_448:
	s_ashr_i32 s6, s12, 3
	s_ashr_i32 s7, s6, 31
	s_and_b32 s1, s12, 7
	s_lshl_b64 s[4:5], s[6:7], 17
	s_lshl_b64 s[6:7], s[6:7], 18
	s_add_u32 s6, s56, s6
	v_readlane_b32 s16, v250, 53
	v_mov_b32_e32 v1, v200
	s_addc_u32 s7, s57, s7
	s_lshl_b32 s2, s1, 18
	v_readlane_b32 s30, v249, 3
	v_readlane_b32 s31, v249, 4
	v_ashrrev_i32_e32 v34, 3, v1
	v_lshlrev_b32_e32 v0, 3, v1
	s_add_u32 s8, s30, s2
	s_waitcnt vmcnt(0)
	v_and_b32_e32 v148, 56, v0
	v_add_u32_e32 v40, 32, v34
	v_add_u32_e32 v46, 64, v34
	v_add_u32_e32 v50, 0x60, v34
	s_addc_u32 s9, s31, 0
	v_lshlrev_b32_e32 v196, 1, v148
	v_ashrrev_i32_e32 v35, 31, v34
	v_ashrrev_i32_e32 v41, 31, v40
	v_ashrrev_i32_e32 v47, 31, v46
	v_ashrrev_i32_e32 v51, 31, v50
	v_lshl_add_u64 v[128:129], s[6:7], 0, v[196:197]
	v_lshl_add_u64 v[130:131], s[8:9], 0, v[196:197]
	v_lshlrev_b64 v[132:133], 11, v[34:35]
	v_lshlrev_b64 v[134:135], 11, v[40:41]
	v_lshlrev_b64 v[136:137], 11, v[46:47]
	v_lshlrev_b64 v[138:139], 11, v[50:51]
	v_lshl_add_u64 v[36:37], v[128:129], 0, v[132:133]
	v_lshl_add_u64 v[38:39], v[130:131], 0, v[132:133]
	v_lshl_add_u64 v[42:43], v[128:129], 0, v[134:135]
	v_lshl_add_u64 v[44:45], v[130:131], 0, v[134:135]
	v_lshl_add_u64 v[48:49], v[128:129], 0, v[136:137]
	v_lshl_add_u64 v[52:53], v[128:129], 0, v[138:139]
	v_lshl_add_u64 v[54:55], v[130:131], 0, v[136:137]
	v_lshl_add_u64 v[56:57], v[130:131], 0, v[138:139]
	v_and_b32_e32 v184, 63, v200
	v_readfirstlane_b32 s2, v200
	v_lshrrev_b32_e32 v185, 3, v184
	v_and_b32_e32 v186, 7, v184
	v_lshrrev_b32_e32 v187, 4, v184
	s_lshr_b32 s2, s2, 6
	v_xor_b32_e32 v186, v186, v187
	v_lshlrev_b32_e32 v186, 4, v186
	v_xor_b32_e32 v187, 64, v186
	s_lshl_b32 s32, s2, 5
	v_add_u32_e32 v185, s32, v185
	v_lshlrev_b32_e32 v188, 11, v185
	v_add_u32_e32 v166, v188, v186
	v_add_u32_e32 v167, v188, v187
	v_add_u32_e32 v168, 0x8000, v166
	v_add_u32_e32 v169, 0x8000, v167
	v_add_u32_e32 v167, 0x4000, v167
	v_add_u32_e32 v169, 0x4000, v169
	v_and_b32_e32 v185, 31, v184
	v_lshrrev_b32_e32 v186, 5, v184
	v_bfe_u32 v187, v184, 1, 3
	v_xor_b32_e32 v186, v186, v187
	v_lshlrev_b32_e32 v186, 4, v186
	v_lshl_add_u32 v186, v185, 7, v186
	s_lshr_b32 s32, s2, 1
	s_lshl_b32 s32, s32, 13
	v_add_u32_e32 v170, s32, v186
	s_and_b32 s32, s2, 1
	s_lshl_b32 s32, s32, 13
	s_add_u32 s32, s32, 0x4000
	v_add_u32_e32 v174, s32, v186
	v_xor_b32_e32 v171, 32, v170
	v_xor_b32_e32 v175, 32, v174
	v_xor_b32_e32 v172, 64, v170
	v_xor_b32_e32 v176, 64, v174
	v_xor_b32_e32 v173, 96, v170
	v_xor_b32_e32 v177, 96, v174
	s_lshl_b32 s32, s2, 12
	s_add_u32 s49, s32, 0x4000
	s_mov_b32 s10, s6
	s_mov_b32 s11, s7
	s_mov_b32 s46, s8
	s_mov_b32 s47, s9
	s_add_u32 m0, s32, 0x0
	s_nop 0
	global_load_lds_dwordx4 v166, s[10:11]
	s_add_u32 m0, m0, 0x400
	s_nop 0
	global_load_lds_dwordx4 v167, s[10:11]
	s_add_u32 m0, m0, 0x400
	s_nop 0
	global_load_lds_dwordx4 v168, s[10:11]
	s_add_u32 m0, m0, 0x400
	s_nop 0
	global_load_lds_dwordx4 v169, s[10:11]
	s_add_u32 m0, s32, 0x4000
	s_nop 0
	global_load_lds_dwordx4 v166, s[46:47]
	s_add_u32 m0, m0, 0x400
	s_nop 0
	global_load_lds_dwordx4 v167, s[46:47]
	s_add_u32 m0, m0, 0x400
	s_nop 0
	global_load_lds_dwordx4 v168, s[46:47]
	s_add_u32 m0, m0, 0x400
	s_nop 0
	global_load_lds_dwordx4 v169, s[46:47]
	s_add_u32 s10, s10, 128
	s_addc_u32 s11, s11, 0
	s_add_u32 s46, s46, 128
	s_addc_u32 s47, s47, 0
	v_and_b32_e32 v58, 31, v1
	v_lshrrev_b32_e32 v59, 1, v1
	v_and_b32_e32 v1, 0x5f, v1
	s_movk_i32 s2, 0x90
	v_and_or_b32 v58, v59, s10, v58
	v_and_b32_e32 v59, 16, v59
	v_mad_u32_u24 v1, v1, s2, 0
	v_mul_lo_u32 v60, v34, s2
	v_mul_lo_u32 v58, v58, s2
	v_add_u32_e32 v149, v1, v59
	v_add_u32_e32 v1, 0, v196
	v_mov_b32_e32 v0, 0
	v_lshlrev_b64 v[34:35], 10, v[34:35]
	v_add_u32_e32 v61, 0x1200, v60
	v_lshlrev_b64 v[40:41], 10, v[40:41]
	v_lshlrev_b64 v[46:47], 10, v[46:47]
	v_lshlrev_b64 v[50:51], 10, v[50:51]
	v_add_u32_e32 v58, 0, v58
	v_add_u32_e32 v150, v1, v60
	s_mov_b32 s13, 0
	s_movk_i32 s14, 0x80
	v_lshlrev_b64 v[140:141], 1, v[34:35]
	v_add_u32_e32 v151, v1, v61
	v_lshlrev_b64 v[142:143], 1, v[40:41]
	v_lshlrev_b64 v[144:145], 1, v[46:47]
	v_lshlrev_b64 v[146:147], 1, v[50:51]
	v_add_u32_e32 v152, v58, v59
	v_mov_b32_e32 v1, v0
	v_mov_b32_e32 v34, v0
	v_mov_b32_e32 v35, v0
	v_mov_b32_e32 v36, v0
	v_mov_b32_e32 v37, v0
	v_mov_b32_e32 v38, v0
	v_mov_b32_e32 v39, v0
	v_mov_b32_e32 v40, v0
	v_mov_b32_e32 v41, v0
	v_mov_b32_e32 v42, v0
	v_mov_b32_e32 v43, v0
	v_mov_b32_e32 v2, v0
	v_mov_b32_e32 v3, v0
	v_mov_b32_e32 v4, v0
	v_mov_b32_e32 v5, v0
	v_mov_b32_e32 v6, v0
	v_mov_b32_e32 v7, v0
	v_mov_b32_e32 v8, v0
	v_mov_b32_e32 v9, v0
	v_mov_b32_e32 v10, v0
	v_mov_b32_e32 v11, v0
	v_mov_b32_e32 v12, v0
	v_mov_b32_e32 v13, v0
	v_mov_b32_e32 v14, v0
	v_mov_b32_e32 v15, v0
	v_mov_b32_e32 v16, v0
	v_mov_b32_e32 v17, v0
	v_mov_b32_e32 v18, v0
	v_mov_b32_e32 v19, v0
	v_mov_b32_e32 v20, v0
	v_mov_b32_e32 v21, v0
	v_mov_b32_e32 v22, v0
	v_mov_b32_e32 v23, v0
	v_mov_b32_e32 v24, v0
	v_mov_b32_e32 v25, v0
	v_mov_b32_e32 v26, v0
	v_mov_b32_e32 v27, v0
	v_mov_b32_e32 v28, v0
	v_mov_b32_e32 v29, v0
	v_mov_b32_e32 v30, v0
	v_mov_b32_e32 v31, v0
	v_mov_b32_e32 v32, v0
	v_mov_b32_e32 v33, v0
	v_mov_b32_e32 v44, v0
	v_mov_b32_e32 v45, v0
	v_mov_b32_e32 v46, v0
	v_mov_b32_e32 v47, v0
	v_mov_b32_e32 v48, v0
	v_mov_b32_e32 v49, v0
	v_mov_b32_e32 v50, v0
	v_mov_b32_e32 v51, v0
	v_mov_b32_e32 v52, v0
	v_mov_b32_e32 v53, v0
	v_mov_b32_e32 v54, v0
	v_mov_b32_e32 v55, v0
	v_mov_b32_e32 v56, v0
	v_mov_b32_e32 v57, v0
	v_mov_b32_e32 v58, v0
	v_mov_b32_e32 v59, v0
	v_mov_b32_e32 v60, v0
	v_mov_b32_e32 v61, v0
	v_mov_b32_e32 v62, v0
	v_mov_b32_e32 v63, v0
	s_mov_b32 s15, 0xfffffc0
	v_readlane_b32 s17, v250, 54
	v_readlane_b32 s18, v250, 55
	v_readlane_b32 s19, v250, 56
	v_readlane_b32 s20, v250, 57
	v_readlane_b32 s21, v250, 58
	v_readlane_b32 s22, v250, 59
	v_readlane_b32 s23, v250, 60
	v_readlane_b32 s24, v250, 61
	v_readlane_b32 s25, v250, 62
	v_readlane_b32 s26, v250, 63
	v_readlane_b32 s27, v249, 0
	v_readlane_b32 s28, v249, 1
	v_readlane_b32 s29, v249, 2
	s_mov_b32 s14, 0x8000
	s_waitcnt vmcnt(0)
	s_waitcnt lgkmcnt(0)
	s_barrier
	s_branch .LBB0_450
.LBB0_450:
	ds_read_b128 v[64:67], v174
	ds_read_b128 v[68:71], v170
	ds_read_b128 v[72:75], v174 offset:4096
	ds_read_b128 v[76:79], v170 offset:4096
	ds_read_b128 v[80:83], v175
	ds_read_b128 v[84:87], v171
	ds_read_b128 v[88:91], v175 offset:4096
	ds_read_b128 v[92:95], v171 offset:4096
	ds_read_b128 v[96:99], v176
	ds_read_b128 v[100:103], v172
	ds_read_b128 v[104:107], v176 offset:4096
	ds_read_b128 v[108:111], v172 offset:4096
	ds_read_b128 v[112:115], v177
	ds_read_b128 v[116:119], v173
	ds_read_b128 v[120:123], v177 offset:4096
	ds_read_b128 v[124:127], v173 offset:4096
	s_add_u32 m0, s32, s14
	s_nop 0
	global_load_lds_dwordx4 v166, s[10:11]
	s_add_u32 m0, m0, 0x400
	s_nop 0
	global_load_lds_dwordx4 v167, s[10:11]
	s_add_u32 m0, m0, 0x400
	s_nop 0
	global_load_lds_dwordx4 v168, s[10:11]
	s_add_u32 m0, m0, 0x400
	s_nop 0
	global_load_lds_dwordx4 v169, s[10:11]
	s_add_u32 m0, s49, s14
	s_nop 0
	global_load_lds_dwordx4 v166, s[46:47]
	s_add_u32 m0, m0, 0x400
	s_nop 0
	global_load_lds_dwordx4 v167, s[46:47]
	s_add_u32 m0, m0, 0x400
	s_nop 0
	global_load_lds_dwordx4 v168, s[46:47]
	s_add_u32 m0, m0, 0x400
	s_nop 0
	global_load_lds_dwordx4 v169, s[46:47]
	s_waitcnt lgkmcnt(14)
	v_mfma_f32_32x32x16_bf16 v[48:63], v[64:67], v[68:71], v[48:63]
	s_waitcnt lgkmcnt(13)
	v_mfma_f32_32x32x16_bf16 v[32:47], v[72:75], v[68:71], v[32:47]
	s_waitcnt lgkmcnt(12)
	v_mfma_f32_32x32x16_bf16 v[16:31], v[64:67], v[76:79], v[16:31]
	v_mfma_f32_32x32x16_bf16 v[0:15], v[72:75], v[76:79], v[0:15]
	s_waitcnt lgkmcnt(10)
	v_mfma_f32_32x32x16_bf16 v[48:63], v[80:83], v[84:87], v[48:63]
	s_waitcnt lgkmcnt(9)
	v_mfma_f32_32x32x16_bf16 v[32:47], v[88:91], v[84:87], v[32:47]
	s_waitcnt lgkmcnt(8)
	v_mfma_f32_32x32x16_bf16 v[16:31], v[80:83], v[92:95], v[16:31]
	v_mfma_f32_32x32x16_bf16 v[0:15], v[88:91], v[92:95], v[0:15]
	s_waitcnt lgkmcnt(6)
	v_mfma_f32_32x32x16_bf16 v[48:63], v[96:99], v[100:103], v[48:63]
	s_waitcnt lgkmcnt(5)
	v_mfma_f32_32x32x16_bf16 v[32:47], v[104:107], v[100:103], v[32:47]
	s_waitcnt lgkmcnt(4)
	v_mfma_f32_32x32x16_bf16 v[16:31], v[96:99], v[108:111], v[16:31]
	v_mfma_f32_32x32x16_bf16 v[0:15], v[104:107], v[108:111], v[0:15]
	s_waitcnt lgkmcnt(2)
	v_mfma_f32_32x32x16_bf16 v[48:63], v[112:115], v[116:119], v[48:63]
	s_waitcnt lgkmcnt(1)
	v_mfma_f32_32x32x16_bf16 v[32:47], v[120:123], v[116:119], v[32:47]
	s_waitcnt lgkmcnt(0)
	v_mfma_f32_32x32x16_bf16 v[16:31], v[112:115], v[124:127], v[16:31]
	v_mfma_f32_32x32x16_bf16 v[0:15], v[120:123], v[124:127], v[0:15]
	v_xor_b32_e32 v170, 0x8000, v170
	v_xor_b32_e32 v171, 0x8000, v171
	v_xor_b32_e32 v172, 0x8000, v172
	v_xor_b32_e32 v173, 0x8000, v173
	v_xor_b32_e32 v174, 0x8000, v174
	v_xor_b32_e32 v175, 0x8000, v175
	v_xor_b32_e32 v176, 0x8000, v176
	v_xor_b32_e32 v177, 0x8000, v177
	s_xor_b32 s14, s14, 0x8000
	s_add_u32 s10, s10, 128
	s_addc_u32 s11, s11, 0
	s_add_u32 s46, s46, 128
	s_addc_u32 s47, s47, 0
	s_add_u32 s13, s13, 1
	s_waitcnt vmcnt(0)
	s_cmp_lt_u32 s13, 15
	s_barrier
	s_cbranch_scc1 .LBB0_450
